# sb_attn band tiles: key-index mask compares use a once-computed (t - base) difference with inline constants, removing 57 v_add per band tile pair
# speedup vs baseline: 1.0024x; 1.0000x over previous
; #define LAS __attribute__((address_space(3)))
; __device__ __forceinline__ int crow(int r, int hi) { return (r & 3) + 8 * (r >> 2) + 4 * hi; }
; __device__ __forceinline__ void sb_qk(const LAS unsigned char* tb, const bf16x8 (&qr)[4], f32x16& p0, f32x16& p1, unsigned krd) {
;     constexpr int KPITCH = 144;
;     p0 = f32x16{}; p1 = f32x16{};
; #pragma unroll
;     for (int d0 = 0; d0 < 4; ++d0) {
;         const bf16x8 a0 = *(const LAS bf16x8*)(tb + krd + d0 * 32);
;         const bf16x8 a1 = *(const LAS bf16x8*)(tb + krd + 32 * KPITCH + d0 * 32);
;         p0 = __builtin_amdgcn_mfma_f32_32x32x16_bf16(a0, qr[d0], p0, 0, 0, 0);
;         p1 = __builtin_amdgcn_mfma_f32_32x32x16_bf16(a1, qr[d0], p1, 0, 0, 0);
;     }
; }
; template <bool BAND> __device__ __forceinline__ void sb_sigma(f32x16& p0, f32x16& p1, int j, int t, int hi) {
; #pragma unroll
;     for (int r = 0; r < 16; ++r) {
;         p0[r] = __builtin_amdgcn_rcpf(1.f + __builtin_amdgcn_exp2f(-p0[r]));
;         p1[r] = __builtin_amdgcn_rcpf(1.f + __builtin_amdgcn_exp2f(-p1[r]));
;     }
;     if (BAND) {
; #pragma unroll
;         for (int r = 0; r < 16; ++r) { const int kv = 64 * j + crow(r, hi); if (kv >= t) p0[r] = 0.f; if (kv + 32 >= t) p1[r] = 0.f; }
;     }
; }
.LBB0_261:
	s_mul_i32 s3, s77, 0x8800
	s_add_i32 s95, s3, 0
	s_add_i32 s3, s93, 0x7f
	s_cmp_ge_i32 s3, s45
	s_mov_b64 s[8:9], -1
	s_cbranch_scc0 .LBB0_265
	s_add_i32 s3, s93, 64
	s_cmp_ge_i32 s3, s94
	s_cbranch_scc1 .LBB0_269
	v_cmp_eq_f32_e32 vcc, 0, v141
	v_mov_b64_e32 v[94:95], v[30:31]
	s_cmp_eq_u64 vcc, exec
	v_mov_b32_e32 v63, v31
	v_mov_b32_e32 v62, v30
	v_mov_b32_e32 v61, v29
	v_mov_b32_e32 v60, v28
	v_mov_b32_e32 v59, v27
	v_mov_b32_e32 v58, v26
	v_mov_b32_e32 v57, v25
	v_mov_b32_e32 v56, v24
	v_mov_b32_e32 v55, v23
	v_mov_b32_e32 v54, v22
	v_mov_b32_e32 v53, v21
	v_mov_b32_e32 v52, v20
	v_mov_b32_e32 v51, v19
	v_mov_b32_e32 v50, v18
	v_mov_b32_e32 v49, v17
	v_mov_b32_e32 v48, v16
	v_mov_b32_e32 v47, v15
	v_mov_b32_e32 v46, v14
	v_mov_b32_e32 v45, v13
	v_mov_b32_e32 v44, v12
	v_mov_b32_e32 v43, v11
	v_mov_b32_e32 v42, v10
	v_mov_b32_e32 v41, v9
	v_mov_b32_e32 v40, v8
	v_mov_b32_e32 v39, v7
	v_mov_b32_e32 v38, v6
	v_mov_b32_e32 v37, v5
	v_mov_b32_e32 v36, v4
	v_mov_b32_e32 v35, v3
	v_mov_b32_e32 v34, v2
	v_mov_b32_e32 v33, v1
	v_mov_b32_e32 v32, v0
	v_mov_b32_e32 v143, v141
	v_mov_b64_e32 v[92:93], v[28:29]
	v_mov_b64_e32 v[90:91], v[26:27]
	v_mov_b64_e32 v[88:89], v[24:25]
	v_mov_b64_e32 v[86:87], v[22:23]
	v_mov_b64_e32 v[84:85], v[20:21]
	v_mov_b64_e32 v[82:83], v[18:19]
	v_mov_b64_e32 v[80:81], v[16:17]
	v_mov_b64_e32 v[78:79], v[14:15]
	v_mov_b64_e32 v[76:77], v[12:13]
	v_mov_b64_e32 v[74:75], v[10:11]
	v_mov_b64_e32 v[72:73], v[8:9]
	v_mov_b64_e32 v[70:71], v[6:7]
	v_mov_b64_e32 v[68:69], v[4:5]
	v_mov_b64_e32 v[66:67], v[2:3]
	v_mov_b64_e32 v[64:65], v[0:1]
	s_cbranch_scc1 .LBB0_270
	v_add_u32_e32 v72, s95, v157
	ds_read_b128 v[32:35], v72 offset:22016
	ds_read_b128 v[36:39], v72 offset:17408
	ds_read_b128 v[64:67], v72 offset:17440
	ds_read_b128 v[68:71], v72 offset:22048
	v_add_u32_e32 v169, s95, v131
	s_waitcnt vmcnt(7) lgkmcnt(2)
	v_mfma_f32_32x32x16_bf16 v[48:63], v[36:39], v[104:107], 0
	v_mfma_f32_32x32x16_bf16 v[32:47], v[32:35], v[104:107], 0
	s_waitcnt vmcnt(6) lgkmcnt(1)
	v_mfma_f32_32x32x16_bf16 v[48:63], v[64:67], v[108:111], v[48:63]
	s_waitcnt lgkmcnt(0)
	v_mfma_f32_32x32x16_bf16 v[32:47], v[68:71], v[108:111], v[32:47]
	ds_read_b128 v[64:67], v72 offset:17472
	ds_read_b128 v[68:71], v72 offset:22080
	s_waitcnt vmcnt(5) lgkmcnt(1)
	v_mfma_f32_32x32x16_bf16 v[48:63], v[64:67], v[112:115], v[48:63]
	s_waitcnt lgkmcnt(0)
	v_mfma_f32_32x32x16_bf16 v[32:47], v[68:71], v[112:115], v[32:47]
	ds_read_b128 v[64:67], v72 offset:17504
	ds_read_b128 v[68:71], v72 offset:22112
	s_waitcnt vmcnt(4) lgkmcnt(1)
	v_mfma_f32_32x32x16_bf16 v[48:63], v[64:67], v[116:119], v[48:63]
	s_waitcnt lgkmcnt(0)
	v_mfma_f32_32x32x16_bf16 v[32:47], v[68:71], v[116:119], v[32:47]
	s_nop 9
	v_exp_f32_e64 v48, -v48
	s_nop 0
	v_add_f32_e32 v48, 1.0, v48
	v_rcp_f32_e32 v65, v48
	v_exp_f32_e64 v32, -v32
	v_exp_f32_e64 v33, -v33
	v_exp_f32_e64 v36, -v36
	v_exp_f32_e64 v37, -v37
	v_add_f32_e32 v32, 1.0, v32
	v_add_f32_e32 v33, 1.0, v33
	v_rcp_f32_e32 v48, v32
	v_exp_f32_e64 v32, -v49
	v_rcp_f32_e32 v49, v33
	v_exp_f32_e64 v33, -v50
	v_exp_f32_e64 v50, -v51
	v_exp_f32_e64 v51, -v52
	v_exp_f32_e64 v52, -v53
	v_exp_f32_e64 v53, -v54
	v_exp_f32_e64 v54, -v55
	v_exp_f32_e64 v55, -v56
	v_exp_f32_e64 v56, -v57
	v_exp_f32_e64 v57, -v58
	v_exp_f32_e64 v58, -v59
	v_exp_f32_e64 v59, -v60
	v_exp_f32_e64 v60, -v61
	v_exp_f32_e64 v61, -v62
	v_exp_f32_e64 v62, -v63
	v_add_u32_e32 v63, s93, v158
	v_sub_u32_e32 v64, v154, v63
	v_subrev_u32_e32 v64, 64, v64
	v_cmp_lt_i32_e64 s[38:39], 0, v64
	v_cmp_lt_i32_e32 vcc, 32, v64
	v_cmp_lt_i32_e64 s[40:41], 1, v64
	v_cmp_lt_i32_e64 s[8:9], 33, v64
	v_cmp_lt_i32_e64 s[42:43], 2, v64
	v_cmp_lt_i32_e64 s[10:11], 34, v64
	v_cmp_lt_i32_e64 s[46:47], 3, v64
	v_cmp_lt_i32_e64 s[12:13], 35, v64
	v_cmp_lt_i32_e64 s[48:49], 8, v64
	v_cmp_lt_i32_e64 s[14:15], 40, v64
	v_cmp_lt_i32_e64 s[50:51], 9, v64
	v_cmp_lt_i32_e64 s[16:17], 41, v64
	v_cmp_lt_i32_e64 s[52:53], 10, v64
	v_cmp_lt_i32_e64 s[18:19], 42, v64
	v_cmp_lt_i32_e64 s[54:55], 11, v64
	v_cmp_lt_i32_e64 s[20:21], 43, v64
	v_cmp_lt_i32_e64 s[56:57], 16, v64
	v_cmp_lt_i32_e64 s[22:23], 48, v64
	v_cmp_lt_i32_e64 s[58:59], 17, v64
	v_cmp_lt_i32_e64 s[24:25], 49, v64
	v_cmp_lt_i32_e64 s[60:61], 18, v64
	v_cmp_lt_i32_e64 s[26:27], 50, v64
	v_cmp_lt_i32_e64 s[62:63], 19, v64
	v_cmp_lt_i32_e64 s[28:29], 51, v64
	v_cmp_lt_i32_e64 s[64:65], 24, v64
	v_cmp_lt_i32_e64 s[30:31], 56, v64
	v_cmp_lt_i32_e64 s[66:67], 25, v64
	v_cmp_lt_i32_e64 s[34:35], 57, v64
	v_cmp_lt_i32_e64 s[68:69], 26, v64
	v_cmp_lt_i32_e64 s[36:37], 58, v64
	v_add_u32_e32 v64, 0x5b, v63
	v_cmp_lt_i32_e64 s[70:71], v64, v154
	s_or_b64 s[68:69], s[70:71], s[68:69]
	s_or_b64 s[66:67], s[68:69], s[66:67]
	s_or_b64 s[64:65], s[66:67], s[64:65]
	s_or_b64 s[62:63], s[64:65], s[62:63]
	s_or_b64 s[60:61], s[62:63], s[60:61]
	s_or_b64 s[58:59], s[60:61], s[58:59]
	s_or_b64 s[56:57], s[58:59], s[56:57]
	s_or_b64 s[54:55], s[56:57], s[54:55]
	s_or_b64 s[52:53], s[54:55], s[52:53]
	v_add_f32_e32 v32, 1.0, v32
	v_add_f32_e32 v50, 1.0, v50
	s_or_b64 s[50:51], s[52:53], s[50:51]
	v_rcp_f32_e32 v32, v32
	v_rcp_f32_e32 v50, v50
	v_add_f32_e32 v53, 1.0, v53
	s_or_b64 s[48:49], s[50:51], s[48:49]
	v_rcp_f32_e32 v53, v53
	s_or_b64 s[46:47], s[48:49], s[46:47]
	s_or_b64 s[42:43], s[46:47], s[42:43]
	s_or_b64 s[40:41], s[42:43], s[40:41]
	v_cndmask_b32_e64 v71, 0, v50, s[46:47]
	v_cndmask_b32_e64 v50, 0, v32, s[40:41]
	s_or_b64 s[38:39], s[40:41], s[38:39]
	v_add_u32_e32 v32, 0x7b, v63
	v_cndmask_b32_e64 v68, 0, v53, s[52:53]
	v_cndmask_b32_e64 v53, 0, v65, s[38:39]
	v_cmp_lt_i32_e64 s[38:39], v32, v154
	s_or_b64 s[36:37], s[38:39], s[36:37]
; __device__ __forceinline__ int crow(int r, int hi) { return (r & 3) + 8 * (r >> 2) + 4 * hi; }
; template <bool BAND> __device__ __forceinline__ void sb_sigma(f32x16& p0, f32x16& p1, int j, int t, int hi) {
; #pragma unroll
;     for (int r = 0; r < 16; ++r) {
;         p0[r] = __builtin_amdgcn_rcpf(1.f + __builtin_amdgcn_exp2f(-p0[r]));
;         p1[r] = __builtin_amdgcn_rcpf(1.f + __builtin_amdgcn_exp2f(-p1[r]));
;     }
;     if (BAND) {
; #pragma unroll
;         for (int r = 0; r < 16; ++r) { const int kv = 64 * j + crow(r, hi); if (kv >= t) p0[r] = 0.f; if (kv + 32 >= t) p1[r] = 0.f; }
;     }
; }
; __device__ __forceinline__ void sb_local(f32x16& p, float (&G)[4]) {
; #pragma unroll
;     for (int g = 0; g < 4; ++g) {
;         const float k0 = 1.f - p[4 * g], k1 = 1.f - p[4 * g + 1], k2 = 1.f - p[4 * g + 2], k3 = 1.f - p[4 * g + 3];
;         const float s2 = k3, s1 = k3 * k2, s0 = s1 * k1;
;         p[4 * g + 2] *= s2; p[4 * g + 1] *= s1; p[4 * g] *= s0; G[g] = s0 * k0;
;     }
; }
	s_or_b64 s[34:35], s[36:37], s[34:35]
	s_or_b64 s[30:31], s[34:35], s[30:31]
	v_exp_f32_e64 v38, -v38
	v_exp_f32_e64 v39, -v39
	s_or_b64 s[28:29], s[30:31], s[28:29]
	v_exp_f32_e64 v47, -v47
	s_or_b64 s[26:27], s[28:29], s[26:27]
	s_or_b64 s[24:25], s[26:27], s[24:25]
	v_add_f32_e32 v33, 1.0, v33
	v_exp_f32_e64 v43, -v43
	s_or_b64 s[22:23], s[24:25], s[22:23]
	v_rcp_f32_e32 v33, v33
	v_add_f32_e32 v36, 1.0, v36
	v_add_f32_e32 v37, 1.0, v37
	v_add_f32_e32 v38, 1.0, v38
	v_add_f32_e32 v39, 1.0, v39
	s_or_b64 s[20:21], s[22:23], s[20:21]
	v_rcp_f32_e32 v36, v36
	v_rcp_f32_e32 v37, v37
	v_rcp_f32_e32 v38, v38
	v_add_f32_e32 v54, 1.0, v54
	v_rcp_f32_e32 v39, v39
	v_exp_f32_e64 v42, -v42
	v_add_f32_e32 v47, 1.0, v47
	s_or_b64 s[18:19], s[20:21], s[18:19]
	v_add_f32_e32 v52, 1.0, v52
	v_rcp_f32_e32 v54, v54
	v_rcp_f32_e32 v47, v47
	s_or_b64 s[16:17], s[18:19], s[16:17]
	v_exp_f32_e64 v34, -v34
	v_exp_f32_e64 v35, -v35
	v_rcp_f32_e32 v52, v52
	v_add_f32_e32 v57, 1.0, v57
	v_add_f32_e32 v58, 1.0, v58
	v_add_f32_e32 v43, 1.0, v43
	s_or_b64 s[14:15], s[16:17], s[14:15]
	v_add_f32_e32 v56, 1.0, v56
	v_rcp_f32_e32 v57, v57
	v_rcp_f32_e32 v58, v58
	v_rcp_f32_e32 v43, v43
	v_exp_f32_e64 v46, -v46
	v_cndmask_b32_e64 v70, 0, v33, s[42:43]
	s_or_b64 s[12:13], s[14:15], s[12:13]
	v_rcp_f32_e32 v56, v56
	v_add_f32_e32 v42, 1.0, v42
	v_add_f32_e32 v61, 1.0, v61
	v_add_f32_e32 v62, 1.0, v62
	v_cndmask_b32_e64 v33, 0, v39, s[20:21]
	v_cndmask_b32_e64 v32, 0, v38, s[18:19]
	v_cndmask_b32_e64 v38, 0, v37, s[16:17]
	v_cndmask_b32_e64 v39, 0, v36, s[14:15]
	s_or_b64 s[10:11], s[12:13], s[10:11]
	v_pk_add_f32 v[36:37], v[70:71], 1.0 op_sel_hi:[1,0] neg_lo:[1,0] neg_hi:[1,0]
	v_rcp_f32_e32 v42, v42
	v_add_f32_e32 v60, 1.0, v60
	v_rcp_f32_e32 v61, v61
	v_rcp_f32_e32 v62, v62
	v_cndmask_b32_e64 v69, 0, v54, s[54:55]
	s_or_b64 s[8:9], s[10:11], s[8:9]
	v_cndmask_b32_e64 v73, 0, v47, s[38:39]
	v_sub_f32_e32 v47, 1.0, v50
	v_mul_f32_e32 v36, v37, v36
	v_add_f32_e32 v34, 1.0, v34
	v_add_f32_e32 v35, 1.0, v35
	v_rcp_f32_e32 v60, v60
	v_cndmask_b32_e64 v52, 0, v52, s[50:51]
	s_or_b64 vcc, s[8:9], vcc
	v_mul_f32_e32 v47, v47, v36
	v_mul_f32_e32 v84, v70, v37
	v_mul_f32_e32 v70, v50, v36
	v_pk_add_f32 v[36:37], v[68:69], 1.0 op_sel_hi:[1,0] neg_lo:[1,0] neg_hi:[1,0]
	v_rcp_f32_e32 v34, v34
	v_rcp_f32_e32 v35, v35
	v_add_f32_e32 v51, 1.0, v51
	v_exp_f32_e64 v41, -v41
	v_add_f32_e32 v46, 1.0, v46
	v_cndmask_b32_e64 v67, 0, v58, s[62:63]
	v_cndmask_b32_e64 v66, 0, v57, s[60:61]
	v_cndmask_b32_e64 v75, 0, v43, s[28:29]
	v_cndmask_b32_e32 v43, 0, v48, vcc
	v_sub_f32_e32 v48, 1.0, v52
	v_mul_f32_e32 v36, v37, v36
	v_rcp_f32_e32 v51, v51
	v_add_f32_e32 v55, 1.0, v55
	v_exp_f32_e64 v40, -v40
	v_rcp_f32_e32 v46, v46
	v_cndmask_b32_e64 v56, 0, v56, s[58:59]
	v_mul_f32_e32 v48, v48, v36
	v_mul_f32_e32 v68, v68, v37
	v_mul_f32_e32 v86, v52, v36
	v_pk_add_f32 v[36:37], v[66:67], 1.0 op_sel_hi:[1,0] neg_lo:[1,0] neg_hi:[1,0]
	v_rcp_f32_e32 v55, v55
	v_add_f32_e32 v59, 1.0, v59
	v_exp_f32_e64 v45, -v45
	v_cndmask_b32_e64 v64, 0, v61, s[68:69]
	v_cndmask_b32_e64 v65, 0, v62, s[70:71]
	v_cndmask_b32_e64 v74, 0, v42, s[26:27]
	v_cndmask_b32_e64 v42, 0, v49, s[8:9]
	v_sub_f32_e32 v49, 1.0, v56
	v_mul_f32_e32 v36, v37, v36
	v_rcp_f32_e32 v59, v59
	v_exp_f32_e64 v44, -v44
	v_cndmask_b32_e64 v60, 0, v60, s[66:67]
	v_mul_f32_e32 v49, v49, v36
	v_mul_f32_e32 v88, v66, v37
	v_mul_f32_e32 v66, v56, v36
	v_pk_add_f32 v[36:37], v[64:65], 1.0 op_sel_hi:[1,0] neg_lo:[1,0] neg_hi:[1,0]
	v_add_f32_e32 v41, 1.0, v41
	v_cndmask_b32_e64 v35, 0, v35, s[12:13]
	v_cndmask_b32_e64 v34, 0, v34, s[10:11]
	v_sub_f32_e32 v50, 1.0, v60
	v_mul_f32_e32 v36, v37, v36
	v_add_f32_e32 v40, 1.0, v40
	v_rcp_f32_e32 v41, v41
	v_cndmask_b32_e64 v51, 0, v51, s[48:49]
	v_cndmask_b32_e64 v72, 0, v46, s[36:37]
	v_sub_f32_e32 v46, 1.0, v53
	v_mul_f32_e32 v50, v50, v36
	v_mul_f32_e32 v64, v64, v37
	v_mul_f32_e32 v90, v60, v36
	v_pk_add_f32 v[36:37], v[34:35], 1.0 op_sel_hi:[1,0] neg_lo:[1,0] neg_hi:[1,0]
	v_rcp_f32_e32 v40, v40
	v_add_f32_e32 v45, 1.0, v45
	v_cndmask_b32_e64 v55, 0, v55, s[56:57]
	v_mul_f32_e32 v85, v53, v47
	v_mul_f32_e32 v46, v46, v47
	v_sub_f32_e32 v47, 1.0, v51
	v_mul_f32_e32 v87, v51, v48
	v_sub_f32_e32 v51, 1.0, v42
	v_mul_f32_e32 v36, v37, v36
	v_add_f32_e32 v44, 1.0, v44
	v_rcp_f32_e32 v45, v45
	v_cndmask_b32_e64 v59, 0, v59, s[64:65]
	v_mul_f32_e32 v47, v47, v48
	v_sub_f32_e32 v48, 1.0, v55
	v_mul_f32_e32 v51, v51, v36
	v_mul_f32_e32 v34, v34, v37
	v_mul_f32_e32 v42, v42, v36
	v_pk_add_f32 v[36:37], v[32:33], 1.0 op_sel_hi:[1,0] neg_lo:[1,0] neg_hi:[1,0]
	v_rcp_f32_e32 v44, v44
	v_mul_f32_e32 v89, v55, v49
	v_mul_f32_e32 v48, v48, v49
	v_sub_f32_e32 v49, 1.0, v59
	v_sub_f32_e32 v52, 1.0, v38
	v_mul_f32_e32 v36, v37, v36
	v_cndmask_b32_e64 v41, 0, v41, s[24:25]
	v_mul_f32_e32 v91, v59, v50
	v_mul_f32_e32 v49, v49, v50
	v_sub_f32_e32 v50, 1.0, v43
	v_mul_f32_e32 v52, v52, v36
	v_mul_f32_e32 v32, v32, v37
	v_mul_f32_e32 v38, v38, v36
	v_pk_add_f32 v[36:37], v[74:75], 1.0 op_sel_hi:[1,0] neg_lo:[1,0] neg_hi:[1,0]
	v_cndmask_b32_e64 v40, 0, v40, s[22:23]
	v_mul_f32_e32 v43, v43, v51
	v_mul_f32_e32 v50, v50, v51
	v_sub_f32_e32 v51, 1.0, v39
	v_sub_f32_e32 v53, 1.0, v41
	v_mul_f32_e32 v36, v37, v36
	v_cndmask_b32_e64 v45, 0, v45, s[34:35]
	v_mul_f32_e32 v39, v39, v52
	v_mul_f32_e32 v51, v51, v52
	v_sub_f32_e32 v52, 1.0, v40
	v_mul_f32_e32 v53, v53, v36
	v_mul_f32_e32 v92, v74, v37
	v_mul_f32_e32 v74, v41, v36
	v_pk_add_f32 v[36:37], v[72:73], 1.0 op_sel_hi:[1,0] neg_lo:[1,0] neg_hi:[1,0]
	v_cndmask_b32_e64 v44, 0, v44, s[30:31]
	v_mul_f32_e32 v93, v40, v53
	v_mul_f32_e32 v40, v52, v53
	v_sub_f32_e32 v52, 1.0, v45
	v_mul_f32_e32 v36, v37, v36
	v_sub_f32_e32 v41, 1.0, v44
	v_mul_f32_e32 v52, v52, v36
	v_mul_f32_e32 v94, v45, v36
	v_mul_f32_e32 v36, v41, v52
	v_mul_f32_e32 v72, v72, v37
	ds_bpermute_b32 v37, v164, v36
	ds_bpermute_b32 v36, v164, v36 offset:128
	ds_bpermute_b32 v41, v164, v50 offset:128
	v_mul_f32_e32 v95, v44, v52
	ds_bpermute_b32 v44, v164, v49 offset:128
	s_waitcnt lgkmcnt(2)
; __device__ __forceinline__ unsigned cvt_pk_bf16(float lo, float hi) { unsigned r; asm volatile("v_cvt_pk_bf16_f32 %0, %1, %2" : "=v"(r) : "v"(lo), "v"(hi)); return r; }
; #define LAS __attribute__((address_space(3)))
; __device__ __forceinline__ void sb_chain(const float (&G1)[4], const float (&G0)[4], float& acc, float (&mine1)[4], float (&mine0)[4], int r32, int hi) {
; #pragma unroll
;     for (int g = 3; g >= 0; --g) {
;         const float gl = __shfl(G1[g], r32), gh = __shfl(G1[g], r32 + 32);
;         const float m1 = acc; acc *= gh; const float m0 = acc; acc *= gl; mine1[g] = hi ? m1 : m0;
;     }
; #pragma unroll
;     for (int g = 3; g >= 0; --g) {
;         const float gl = __shfl(G0[g], r32), gh = __shfl(G0[g], r32 + 32);
;         const float m1 = acc; acc *= gh; const float m0 = acc; acc *= gl; mine0[g] = hi ? m1 : m0;
;     }
; }
; __device__ __forceinline__ void sb_pv(const LAS unsigned char* tb, const f32x16& p0, const f32x16& p1, const float (&mine0)[4], const float (&mine1)[4], f32x16 (&o)[2], unsigned vrd) {
; #pragma unroll
;     for (int X = 1; X >= 0; --X)
; #pragma unroll
;         for (int s = 0; s < 2; ++s) {
;             u32x4 pw;
;     ...
;             pw.x = pg8::cvt_pk_bf16(AV(0), AV(1)); pw.y = pg8::cvt_pk_bf16(AV(2), AV(3)); pw.z = pg8::cvt_pk_bf16(AV(4), AV(5)); pw.w = pg8::cvt_pk_bf16(AV(6), AV(7));
;     ...
;             const bf16x8 pf = __builtin_bit_cast(bf16x8, pw);
; #pragma unroll
;             for (int c = 0; c < 2; ++c) {
;                 const LAS unsigned char* vp = tb + vrd + ((8 * X + 4 * s) * 4 + 2 * c) * 128;
;                 const s16x4 lo = __builtin_bit_cast(s16x4, __builtin_amdgcn_ds_read_tr16_b64_v4i16((LAS s16x4*)(vp)));
;                 const s16x4 hh = __builtin_bit_cast(s16x4, __builtin_amdgcn_ds_read_tr16_b64_v4i16((LAS s16x4*)(vp + 2 * 4 * 128)));
;                 const bf16x8 vf = (bf16x8){lo[0], lo[1], lo[2], lo[3], hh[0], hh[1], hh[2], hh[3]};
;                 o[c] = __builtin_amdgcn_mfma_f32_32x32x16_bf16(vf, pf, o[c], 0, 0, 0);
;             }
;         }
	v_mul_f32_e32 v36, v141, v36
	v_mul_f32_e32 v37, v36, v37
	v_cndmask_b32_e64 v145, v141, v36, s[4:5]
	ds_bpermute_b32 v36, v164, v40
	ds_bpermute_b32 v40, v164, v40 offset:128
	v_mul_f32_e32 v72, v145, v72
	v_mul_f32_e32 v73, v145, v73
	s_waitcnt lgkmcnt(0)
	v_mul_f32_e32 v40, v37, v40
	v_mul_f32_e32 v36, v40, v36
	v_cndmask_b32_e64 v155, v37, v40, s[4:5]
	ds_bpermute_b32 v40, v164, v51 offset:128
	ds_bpermute_b32 v37, v164, v51
	v_mul_f32_e32 v74, v155, v74
	v_mul_f32_e32 v75, v155, v75
	s_waitcnt lgkmcnt(1)
	v_mul_f32_e32 v40, v36, v40
	s_waitcnt lgkmcnt(0)
	v_mul_f32_e32 v37, v40, v37
	v_cndmask_b32_e64 v36, v36, v40, s[4:5]
	ds_bpermute_b32 v40, v164, v50
	v_mul_f32_e32 v41, v37, v41
	v_cndmask_b32_e64 v37, v37, v41, s[4:5]
	v_mul_f32_e32 v34, v37, v34
	v_mul_f32_e32 v35, v37, v35
	s_waitcnt lgkmcnt(0)
	v_mul_f32_e32 v40, v41, v40
	ds_bpermute_b32 v41, v164, v49
	v_mul_f32_e32 v44, v40, v44
	v_cndmask_b32_e64 v165, v40, v44, s[4:5]
	ds_bpermute_b32 v40, v164, v48
	v_mul_f32_e32 v32, v36, v32
	s_waitcnt lgkmcnt(1)
	v_mul_f32_e32 v41, v44, v41
	ds_bpermute_b32 v44, v164, v48 offset:128
	v_mul_f32_e32 v33, v36, v33
	v_mul_f32_e32 v65, v165, v65
	v_mul_f32_e32 v64, v165, v64
	s_waitcnt lgkmcnt(0)
	v_mul_f32_e32 v44, v41, v44
	v_mul_f32_e32 v40, v44, v40
	v_cndmask_b32_e64 v166, v41, v44, s[4:5]
	ds_bpermute_b32 v44, v164, v47 offset:128
	ds_bpermute_b32 v41, v164, v47
	v_mul_f32_e32 v66, v166, v66
	v_mul_f32_e32 v67, v166, v67
	s_waitcnt lgkmcnt(1)
	v_mul_f32_e32 v44, v40, v44
	s_waitcnt lgkmcnt(0)
	v_mul_f32_e32 v41, v44, v41
	v_cndmask_b32_e64 v167, v40, v44, s[4:5]
	ds_bpermute_b32 v44, v164, v46 offset:128
	ds_bpermute_b32 v40, v164, v46
	v_mul_f32_e32 v68, v167, v68
	v_mul_f32_e32 v69, v167, v69
	s_waitcnt lgkmcnt(1)
	v_mul_f32_e32 v44, v41, v44
	s_waitcnt lgkmcnt(0)
	v_mul_f32_e32 v143, v44, v40
	v_cndmask_b32_e64 v168, v41, v44, s[4:5]
	v_mul_f32_e32 v40, v37, v43
	v_mul_f32_e32 v41, v37, v42
	v_cvt_pk_bf16_f32 v76, v40, v41
	v_cvt_pk_bf16_f32 v77, v34, v35
	v_mul_f32_e32 v34, v36, v39
	v_mul_f32_e32 v35, v36, v38
	v_cvt_pk_bf16_f32 v78, v34, v35
	v_cvt_pk_bf16_f32 v79, v32, v33
	ds_read_b64_tr_b16 v[48:49], v169 offset:30720
	ds_read_b64_tr_b16 v[50:51], v169 offset:31744
	ds_read_b64_tr_b16 v[80:81], v169 offset:30976
	ds_read_b64_tr_b16 v[82:83], v169 offset:32000
	v_mov_b64_e32 v[46:47], v[14:15]
	v_mov_b64_e32 v[44:45], v[12:13]
	v_mov_b64_e32 v[42:43], v[10:11]
	v_mov_b64_e32 v[40:41], v[8:9]
	v_mov_b64_e32 v[38:39], v[6:7]
	v_mov_b64_e32 v[36:37], v[4:5]
	v_mov_b64_e32 v[34:35], v[2:3]
	v_mov_b64_e32 v[32:33], v[0:1]
	v_mul_f32_e32 v70, v168, v70
	v_mul_f32_e32 v71, v168, v71
	s_waitcnt lgkmcnt(2)
	v_mfma_f32_32x32x16_bf16 v[32:47], v[48:51], v[76:79], v[32:47]
	v_mov_b64_e32 v[62:63], v[30:31]
	v_mov_b64_e32 v[60:61], v[28:29]
	v_mov_b64_e32 v[58:59], v[26:27]
	v_mov_b64_e32 v[56:57], v[24:25]
	v_mov_b64_e32 v[54:55], v[22:23]
	v_mov_b64_e32 v[52:53], v[20:21]
	v_mov_b64_e32 v[50:51], v[18:19]
	v_mov_b64_e32 v[48:49], v[16:17]
	s_waitcnt lgkmcnt(0)
	s_nop 0
	v_mfma_f32_32x32x16_bf16 v[48:63], v[80:83], v[76:79], v[48:63]
	v_mul_f32_e32 v76, v155, v93
	v_cvt_pk_bf16_f32 v74, v76, v74
	v_mul_f32_e32 v76, v155, v92
	v_cvt_pk_bf16_f32 v75, v76, v75
	v_mul_f32_e32 v76, v145, v95
	v_mul_f32_e32 v77, v145, v94
	v_cvt_pk_bf16_f32 v76, v76, v77
	v_cvt_pk_bf16_f32 v77, v72, v73
	ds_read_b64_tr_b16 v[78:79], v169 offset:32768
	ds_read_b64_tr_b16 v[80:81], v169 offset:33792
	s_waitcnt lgkmcnt(0)
	v_mfma_f32_32x32x16_bf16 v[32:47], v[78:81], v[74:77], v[32:47]
	ds_read_b64_tr_b16 v[78:79], v169 offset:33024
	ds_read_b64_tr_b16 v[80:81], v169 offset:34048
	v_mul_f32_e32 v72, v168, v85
	v_cvt_pk_bf16_f32 v70, v72, v70
	v_mul_f32_e32 v72, v168, v84
	v_cvt_pk_bf16_f32 v71, v72, v71
	v_mul_f32_e32 v72, v167, v87
	v_mul_f32_e32 v73, v167, v86
	s_waitcnt lgkmcnt(0)
	v_mfma_f32_32x32x16_bf16 v[48:63], v[78:81], v[74:77], v[48:63]
	v_cvt_pk_bf16_f32 v72, v72, v73
	v_cvt_pk_bf16_f32 v73, v68, v69
	ds_read_b64_tr_b16 v[74:75], v169 offset:26624
	ds_read_b64_tr_b16 v[76:77], v169 offset:27648
	v_mul_f32_e32 v68, v166, v89
	v_mul_f32_e32 v69, v165, v90
	s_waitcnt lgkmcnt(0)
	v_mfma_f32_32x32x16_bf16 v[32:47], v[74:77], v[70:73], v[32:47]
	ds_read_b64_tr_b16 v[74:75], v169 offset:26880
	ds_read_b64_tr_b16 v[76:77], v169 offset:27904
	v_cvt_pk_bf16_f32 v66, v68, v66
	v_mul_f32_e32 v68, v166, v88
	v_cvt_pk_bf16_f32 v67, v68, v67
	v_mul_f32_e32 v68, v165, v91
	v_cvt_pk_bf16_f32 v68, v68, v69
	v_cvt_pk_bf16_f32 v69, v64, v65
	s_waitcnt lgkmcnt(0)
	v_mfma_f32_32x32x16_bf16 v[48:63], v[74:77], v[70:73], v[48:63]
	ds_read_b64_tr_b16 v[70:71], v169 offset:28672
	ds_read_b64_tr_b16 v[72:73], v169 offset:29696
	s_waitcnt lgkmcnt(0)
	v_mfma_f32_32x32x16_bf16 v[32:47], v[70:73], v[66:69], v[32:47]
	ds_read_b64_tr_b16 v[70:71], v169 offset:28928
	ds_read_b64_tr_b16 v[72:73], v169 offset:29952
	s_waitcnt lgkmcnt(0)
	v_mfma_f32_32x32x16_bf16 v[48:63], v[70:73], v[66:69], v[48:63]
	s_nop 11
	v_mov_b64_e32 v[94:95], v[62:63]
	v_mov_b64_e32 v[92:93], v[60:61]
	v_mov_b64_e32 v[90:91], v[58:59]
	v_mov_b64_e32 v[88:89], v[56:57]
	v_mov_b64_e32 v[86:87], v[54:55]
	v_mov_b64_e32 v[84:85], v[52:53]
	v_mov_b64_e32 v[82:83], v[50:51]
	v_mov_b64_e32 v[80:81], v[48:49]
	v_mov_b64_e32 v[78:79], v[46:47]
	v_mov_b64_e32 v[76:77], v[44:45]
	v_mov_b64_e32 v[74:75], v[42:43]
	v_mov_b64_e32 v[72:73], v[40:41]
	v_mov_b64_e32 v[70:71], v[38:39]
	v_mov_b64_e32 v[68:69], v[36:37]
	v_mov_b64_e32 v[66:67], v[34:35]
	v_mov_b64_e32 v[64:65], v[32:33]
	s_branch .LBB0_270

; #define LAS __attribute__((address_space(3)))
; __device__ __forceinline__ void sb_qk(const LAS unsigned char* tb, const bf16x8 (&qr)[4], f32x16& p0, f32x16& p1, unsigned krd) {
;     constexpr int KPITCH = 144;
;     p0 = f32x16{}; p1 = f32x16{};
; #pragma unroll
;     for (int d0 = 0; d0 < 4; ++d0) {
;         const bf16x8 a0 = *(const LAS bf16x8*)(tb + krd + d0 * 32);
;         const bf16x8 a1 = *(const LAS bf16x8*)(tb + krd + 32 * KPITCH + d0 * 32);
;         p0 = __builtin_amdgcn_mfma_f32_32x32x16_bf16(a0, qr[d0], p0, 0, 0, 0);
;         p1 = __builtin_amdgcn_mfma_f32_32x32x16_bf16(a1, qr[d0], p1, 0, 0, 0);
;     }
; }
; template <bool BAND> __device__ __forceinline__ void sb_sigma(f32x16& p0, f32x16& p1, int j, int t, int hi) {
; #pragma unroll
;     for (int r = 0; r < 16; ++r) {
;         p0[r] = __builtin_amdgcn_rcpf(1.f + __builtin_amdgcn_exp2f(-p0[r]));
;         p1[r] = __builtin_amdgcn_rcpf(1.f + __builtin_amdgcn_exp2f(-p1[r]));
;     }
; __device__ __forceinline__ void sb_tile(const LAS unsigned char* tb, int j, const bf16x8 (&qr)[4], f32x16 (&o)[2], float& Rp, int t, int tq0, int r32, int hi, unsigned krd, unsigned vrd) {
;     if (!(64 * j < tq0 + 31)) return;
;     if (__all(Rp == 0.f)) return;
;     f32x16 p0, p1; float G0[4], G1[4], mine0[4], mine1[4];
;     sb_qk(tb, qr, p0, p1, krd);
;     if (64 * j + 63 >= tq0) sb_sigma<true>(p0, p1, j, t, hi); else sb_sigma<false>(p0, p1, j, t, hi);
.LBB0_270:
	s_cmp_ge_i32 s93, s94
	s_cbranch_scc1 .LBB0_275
	v_cmp_eq_f32_e32 vcc, 0, v143
	s_cmp_eq_u64 vcc, exec
	s_cbranch_scc1 .LBB0_275
	v_add_u32_e32 v145, s95, v157
	ds_read_b128 v[32:35], v145
	ds_read_b128 v[166:169], v145 offset:32
	ds_read_b128 v[48:51], v145 offset:4608
	ds_read_b128 v[170:173], v145 offset:4640
	s_add_i32 s3, s93, 63
	s_cmp_lt_i32 s3, s45
	s_waitcnt vmcnt(7) lgkmcnt(3)
	v_mfma_f32_32x32x16_bf16 v[32:47], v[32:35], v[104:107], 0
	s_waitcnt lgkmcnt(1)
	v_mfma_f32_32x32x16_bf16 v[48:63], v[48:51], v[104:107], 0
	s_waitcnt vmcnt(6)
	v_mfma_f32_32x32x16_bf16 v[32:47], v[166:169], v[108:111], v[32:47]
	s_waitcnt lgkmcnt(0)
	v_mfma_f32_32x32x16_bf16 v[48:63], v[170:173], v[108:111], v[48:63]
	ds_read_b128 v[166:169], v145 offset:64
	ds_read_b128 v[170:173], v145 offset:96
	s_waitcnt vmcnt(5) lgkmcnt(1)
	v_mfma_f32_32x32x16_bf16 v[32:47], v[166:169], v[112:115], v[32:47]
	ds_read_b128 v[166:169], v145 offset:4672
	ds_read_b128 v[174:177], v145 offset:4704
	s_waitcnt lgkmcnt(1)
	v_mfma_f32_32x32x16_bf16 v[48:63], v[166:169], v[112:115], v[48:63]
	s_waitcnt vmcnt(4)
	v_mfma_f32_32x32x16_bf16 v[32:47], v[170:173], v[116:119], v[32:47]
	s_waitcnt lgkmcnt(0)
	v_mfma_f32_32x32x16_bf16 v[48:63], v[174:177], v[116:119], v[48:63]
	s_nop 9
	v_exp_f32_e64 v32, -v32
	s_nop 0
	v_add_f32_e32 v32, 1.0, v32
	v_rcp_f32_e32 v167, v32
	v_exp_f32_e64 v32, -v33
	v_exp_f32_e64 v48, -v48
	v_add_f32_e32 v32, 1.0, v32
	v_add_f32_e32 v33, 1.0, v48
	v_rcp_f32_e32 v145, v33
	v_exp_f32_e64 v33, -v49
	v_rcp_f32_e32 v168, v32
	v_exp_f32_e64 v32, -v34
	v_exp_f32_e64 v34, -v35
	v_add_f32_e32 v33, 1.0, v33
	v_rcp_f32_e32 v155, v33
	v_exp_f32_e64 v33, -v50
	v_exp_f32_e64 v35, -v51
	v_add_f32_e32 v32, 1.0, v32
	v_rcp_f32_e32 v32, v32
	v_add_f32_e32 v33, 1.0, v33
	v_rcp_f32_e32 v48, v33
	v_add_f32_e32 v33, 1.0, v34
	v_exp_f32_e64 v34, -v36
	v_add_f32_e32 v35, 1.0, v35
	v_rcp_f32_e32 v49, v35
	v_exp_f32_e64 v35, -v52
	v_add_f32_e32 v34, 1.0, v34
	v_rcp_f32_e32 v169, v34
	v_exp_f32_e64 v34, -v37
	v_exp_f32_e64 v37, -v55
	v_add_f32_e32 v35, 1.0, v35
	v_rcp_f32_e32 v165, v35
	v_exp_f32_e64 v35, -v53
	v_add_f32_e32 v37, 1.0, v37
	v_rcp_f32_e32 v51, v37
	v_exp_f32_e64 v37, -v56
	v_add_f32_e32 v35, 1.0, v35
	v_rcp_f32_e32 v166, v35
	v_exp_f32_e64 v35, -v54
	v_add_f32_e32 v37, 1.0, v37
	v_rcp_f32_e32 v56, v37
	v_exp_f32_e64 v37, -v57
	v_exp_f32_e64 v36, -v39
	v_add_f32_e32 v35, 1.0, v35
	v_add_f32_e32 v34, 1.0, v34
	v_add_f32_e32 v37, 1.0, v37
	v_rcp_f32_e32 v50, v35
	v_add_f32_e32 v35, 1.0, v36
	v_exp_f32_e64 v36, -v40
	v_rcp_f32_e32 v57, v37
	v_exp_f32_e64 v37, -v58
	v_exp_f32_e64 v39, -v59
	v_rcp_f32_e32 v170, v34
	v_exp_f32_e64 v34, -v38
	v_exp_f32_e64 v38, -v43
	v_add_f32_e32 v36, 1.0, v36
	v_add_f32_e32 v37, 1.0, v37
	v_add_f32_e32 v39, 1.0, v39
	v_rcp_f32_e32 v52, v36
	v_exp_f32_e64 v36, -v41
	v_rcp_f32_e32 v40, v37
	v_add_f32_e32 v37, 1.0, v38
	v_exp_f32_e64 v38, -v44
	v_rcp_f32_e32 v41, v39
	v_exp_f32_e64 v39, -v60
	v_add_f32_e32 v36, 1.0, v36
	v_add_f32_e32 v38, 1.0, v38
	v_rcp_f32_e32 v54, v38
	v_add_f32_e32 v39, 1.0, v39
	v_exp_f32_e64 v38, -v45
	v_rcp_f32_e32 v58, v39
	v_exp_f32_e64 v39, -v61
	v_rcp_f32_e32 v53, v36
	v_add_f32_e32 v38, 1.0, v38
	v_rcp_f32_e32 v55, v38
	v_add_f32_e32 v39, 1.0, v39
	v_exp_f32_e64 v38, -v46
	v_rcp_f32_e32 v46, v39
	v_exp_f32_e64 v39, -v62
	v_exp_f32_e64 v36, -v42
	v_exp_f32_e64 v43, -v47
	v_exp_f32_e64 v44, -v63
	v_add_f32_e32 v39, 1.0, v39
	v_add_f32_e32 v34, 1.0, v34
	v_add_f32_e32 v36, 1.0, v36
	v_add_f32_e32 v38, 1.0, v38
	v_rcp_f32_e32 v42, v39
	v_add_f32_e32 v39, 1.0, v43
	v_add_f32_e32 v43, 1.0, v44
	v_rcp_f32_e32 v33, v33
	v_rcp_f32_e32 v34, v34
	v_rcp_f32_e32 v35, v35
	v_rcp_f32_e32 v36, v36
	v_rcp_f32_e32 v37, v37
	v_rcp_f32_e32 v38, v38
	v_rcp_f32_e32 v39, v39
	v_rcp_f32_e32 v43, v43
	s_cbranch_scc1 .LBB0_274
; __device__ __forceinline__ int crow(int r, int hi) { return (r & 3) + 8 * (r >> 2) + 4 * hi; }
; template <bool BAND> __device__ __forceinline__ void sb_sigma(f32x16& p0, f32x16& p1, int j, int t, int hi) {
; #pragma unroll
;     for (int r = 0; r < 16; ++r) {
;         p0[r] = __builtin_amdgcn_rcpf(1.f + __builtin_amdgcn_exp2f(-p0[r]));
;         p1[r] = __builtin_amdgcn_rcpf(1.f + __builtin_amdgcn_exp2f(-p1[r]));
;     }
;     if (BAND) {
; #pragma unroll
;         for (int r = 0; r < 16; ++r) { const int kv = 64 * j + crow(r, hi); if (kv >= t) p0[r] = 0.f; if (kv + 32 >= t) p1[r] = 0.f; }
;     }
; }
	v_add_u32_e32 v44, s93, v158
	v_sub_u32_e32 v45, v154, v44
	v_cmp_lt_i32_e32 vcc, 32, v45
	v_cmp_lt_i32_e64 s[34:35], 1, v45
	v_cmp_lt_i32_e64 s[8:9], 33, v45
	v_cmp_lt_i32_e64 s[38:39], 2, v45
	v_cmp_lt_i32_e64 s[10:11], 34, v45
	v_cmp_lt_i32_e64 s[42:43], 3, v45
	v_cmp_lt_i32_e64 s[12:13], 35, v45
	v_cmp_lt_i32_e64 s[46:47], 8, v45
	v_cmp_lt_i32_e64 s[14:15], 40, v45
	v_cmp_lt_i32_e64 s[48:49], 9, v45
	v_cmp_lt_i32_e64 s[16:17], 41, v45
	v_cmp_lt_i32_e64 s[50:51], 10, v45
	v_cmp_lt_i32_e64 s[18:19], 42, v45
	v_cmp_lt_i32_e64 s[52:53], 11, v45
	v_cmp_lt_i32_e64 s[20:21], 43, v45
	v_cmp_lt_i32_e64 s[54:55], 16, v45
	v_cmp_lt_i32_e64 s[22:23], 48, v45
	v_cmp_lt_i32_e64 s[56:57], 17, v45
	v_cmp_lt_i32_e64 s[24:25], 49, v45
	v_cmp_lt_i32_e64 s[58:59], 18, v45
	v_cmp_lt_i32_e64 s[26:27], 50, v45
	v_cmp_lt_i32_e64 s[60:61], 19, v45
	v_cmp_lt_i32_e64 s[30:31], 51, v45
	v_cmp_lt_i32_e64 s[62:63], 24, v45
	v_cmp_lt_i32_e64 s[36:37], 56, v45
	v_cmp_lt_i32_e64 s[64:65], 25, v45
	v_cmp_lt_i32_e64 s[40:41], 57, v45
	v_cmp_lt_i32_e64 s[66:67], 26, v45
	v_cmp_lt_i32_e64 s[68:69], 58, v45
	v_add_u32_e32 v45, 27, v44
	v_cmp_lt_i32_e64 s[70:71], v45, v154
	s_or_b64 s[66:67], s[70:71], s[66:67]
	s_or_b64 s[64:65], s[66:67], s[64:65]
	s_or_b64 s[62:63], s[64:65], s[62:63]
	s_or_b64 s[60:61], s[62:63], s[60:61]
	s_or_b64 s[58:59], s[60:61], s[58:59]
	s_or_b64 s[56:57], s[58:59], s[56:57]
	s_or_b64 s[54:55], s[56:57], s[54:55]
	s_or_b64 s[52:53], s[54:55], s[52:53]
	s_or_b64 s[50:51], s[52:53], s[50:51]
	s_or_b64 s[48:49], s[50:51], s[48:49]
	s_or_b64 s[46:47], s[48:49], s[46:47]
	s_or_b64 s[42:43], s[46:47], s[42:43]
	s_or_b64 s[38:39], s[42:43], s[38:39]
	v_cmp_lt_i32_e64 s[28:29], v44, v154
	s_or_b64 s[34:35], s[38:39], s[34:35]
	s_or_b64 s[28:29], s[34:35], s[28:29]
	v_add_u32_e32 v44, 59, v44
	v_cndmask_b32_e64 v167, 0, v167, s[28:29]
	v_cmp_lt_i32_e64 s[28:29], v44, v154
	v_cndmask_b32_e64 v39, 0, v39, s[70:71]
	v_cndmask_b32_e64 v38, 0, v38, s[66:67]
	v_cndmask_b32_e64 v43, 0, v43, s[28:29]
	s_or_b64 s[28:29], s[28:29], s[68:69]
	v_cndmask_b32_e64 v42, 0, v42, s[28:29]
	s_or_b64 s[28:29], s[28:29], s[40:41]
	v_cndmask_b32_e64 v46, 0, v46, s[28:29]
	s_or_b64 s[28:29], s[28:29], s[36:37]
	v_cndmask_b32_e64 v58, 0, v58, s[28:29]
	s_or_b64 s[28:29], s[28:29], s[30:31]
	s_or_b64 s[26:27], s[28:29], s[26:27]
	s_or_b64 s[24:25], s[26:27], s[24:25]
	s_or_b64 s[22:23], s[24:25], s[22:23]
	s_or_b64 s[20:21], s[22:23], s[20:21]
	s_or_b64 s[18:19], s[20:21], s[18:19]
	s_or_b64 s[16:17], s[18:19], s[16:17]
	s_or_b64 s[14:15], s[16:17], s[14:15]
	s_or_b64 s[12:13], s[14:15], s[12:13]
	s_or_b64 s[10:11], s[12:13], s[10:11]
	s_or_b64 s[8:9], s[10:11], s[8:9]
	s_or_b64 vcc, s[8:9], vcc
	v_cndmask_b32_e64 v55, 0, v55, s[64:65]
	v_cndmask_b32_e64 v54, 0, v54, s[62:63]
	v_cndmask_b32_e64 v37, 0, v37, s[60:61]
	v_cndmask_b32_e64 v36, 0, v36, s[58:59]
	v_cndmask_b32_e64 v53, 0, v53, s[56:57]
	v_cndmask_b32_e64 v52, 0, v52, s[54:55]
	v_cndmask_b32_e64 v35, 0, v35, s[52:53]
	v_cndmask_b32_e64 v34, 0, v34, s[50:51]
	v_cndmask_b32_e64 v170, 0, v170, s[48:49]
	v_cndmask_b32_e64 v169, 0, v169, s[46:47]
	v_cndmask_b32_e64 v33, 0, v33, s[42:43]
	v_cndmask_b32_e64 v32, 0, v32, s[38:39]
	v_cndmask_b32_e64 v168, 0, v168, s[34:35]
	v_cndmask_b32_e64 v41, 0, v41, s[28:29]
	v_cndmask_b32_e64 v40, 0, v40, s[26:27]
	v_cndmask_b32_e64 v57, 0, v57, s[24:25]
	v_cndmask_b32_e64 v56, 0, v56, s[22:23]
	v_cndmask_b32_e64 v51, 0, v51, s[20:21]
	v_cndmask_b32_e64 v50, 0, v50, s[18:19]
	v_cndmask_b32_e64 v166, 0, v166, s[16:17]
	v_cndmask_b32_e64 v165, 0, v165, s[14:15]
	v_cndmask_b32_e64 v49, 0, v49, s[12:13]
	v_cndmask_b32_e64 v48, 0, v48, s[10:11]
	v_cndmask_b32_e64 v155, 0, v155, s[8:9]
	v_cndmask_b32_e32 v145, 0, v145, vcc
